# GEMM per-phase s_setprio flips deleted plus one static s_setprio 1 for waves 0-3 in all non-attention phases (reset to 0 inside the attention phase)
# baseline (speedup 1.0000x reference)
; __global__ void __launch_bounds__(512, 2) mega(Params p) {
;     ...
;   for (int layer = 0; layer < 4; ++layer) {
;     const int kind = layer % 3, j = layer / 3;
;     const float* xin = (layer == 0) ? p.x : p.out;
;     unsigned char* H8 = (unsigned char*)(ws + ((kind == 0) ? OFF_KV + 67108864 : OFF_Y));
;     rmsnorm_rows<false>(xin, p.norm_in + layer * 2048, H, NTOK, H8);
.LBB0_36:
	v_readfirstlane_b32 s100, v179
	s_nop 3
	s_cmp_ge_u32 s100, 0x100
	s_cbranch_scc1 .Lprio_layer
	s_setprio 1

; __global__ void __launch_bounds__(512, 2) mega(Params p) {
;     ...
;     {
;       const int nself = (kind == 0) ? 1024 : 2048, total = nself + 512;
;       const u16* mgb = (kind == 0) ? MG : Pb;
;       const int ldmg = (kind == 0) ? 4096 : (kind == 1 ? 7808 : 6656);
;       const int mqcol = (kind == 0) ? 0 : (kind == 1 ? 3664 : 2560);
;       const int gatecol = (kind == 0) ? 1024 : (kind == 1 ? 4688 : 3584);
;       const u16* memkv = MEMKV + layer * 2048;
;       float* lut_all = (float*)(smem + LDS_LUT);
;       if (kind != 0) {
;         for (int i = tid; i < 32 * 129; i += 512) { const int h = i / 129, r = i - h * 129; lut_all[h * 132 + r] = LUT[r * 32 + h]; }
;       }
;       if (tid == 0) s_item[0] = atomicAdd(&CTR[layer], 1);
;       __syncthreads();
;       for (int par = 0;; par ^= 1) {
;         const int item = __builtin_amdgcn_readfirstlane(s_item[par]);
.LBB0_1237:
	s_or_b64 exec, exec, s[0:1]
	s_or_b32 s23, s22, 0x200
	v_readlane_b32 s0, v254, 51
	s_cmp_lg_u32 s0, 1
	s_cselect_b64 s[66:67], -1, 0
	s_cmp_eq_u32 s0, 1
	s_movk_i32 s0, 0x1a00
	s_cselect_b32 s8, 0x1e80, s0
	s_movk_i32 s0, 0xe50
	s_cselect_b32 s9, s0, 0xa00
	s_movk_i32 s0, 0x1250
	s_cselect_b32 s10, s0, 0xe00
	v_readlane_b32 s0, v254, 52
	v_readlane_b32 s1, v254, 53
	s_and_b64 s[0:1], s[0:1], exec
	v_readlane_b32 s0, v254, 54
	s_cselect_b32 s24, 0x1000, s8
	s_cselect_b32 s8, 0, s9
	s_cselect_b32 s9, 0x400, s10
	v_readlane_b32 s1, v254, 55
	s_lshl_b32 s0, s0, 1
	s_add_u32 s59, s76, s0
	v_readlane_b32 s0, v254, 41
	v_readlane_b32 s1, v254, 42
	s_addc_u32 s65, s77, 0
	s_lshl_b64 s[0:1], s[0:1], 2
	v_readlane_b32 s10, v250, 48
	s_add_u32 s78, s10, s0
	v_readlane_b32 s0, v250, 49
	s_addc_u32 s79, s0, s1
	v_readlane_b32 s0, v254, 45
	v_readlane_b32 s1, v254, 46
	s_and_b64 s[0:1], s[0:1], exec
	s_mov_b32 s25, 0
	s_cselect_b32 s85, 32, 0
	s_lshl_b32 s72, s8, 1
	s_lshl_b32 s68, s9, 1
	s_setprio 0
	s_waitcnt lgkmcnt(0)
	s_barrier
	s_branch .LBB0_1241
